# SwiGLU epilogue: bf16 tile staged through LDS and written as full 256-B row segments (8 dwordx4 stores per wave) instead of 16 dwordx2 stores touching 16 rows each; +16 KiB static LDS
# speedup vs baseline: 1.0085x; 1.0085x over previous
.LBB0_736:
	v_mov_b32_e32 v140, v145
	s_mov_b32 s17, s79
	v_mov_b32_e32 v141, v144
	s_mov_b32 s19, s62
	s_lshl_b32 s24, s24, 8
	s_lshl_b32 s19, s19, 6
	s_add_i32 s19, s19, s24
	v_add_u32_e32 v148, s19, v141
	s_lshl_b32 s19, s25, 7
	s_lshl_b32 s17, s17, 4
	s_add_i32 s17, s17, s19
	v_lshl_add_u32 v142, v140, 2, s17
	v_ashrrev_i32_e32 v143, 31, v142
	v_mov_b64_e32 v[140:141], s[6:7]
	v_mad_i64_i32 v[150:151], s[24:25], v148, s47, v[140:141]
	v_lshlrev_b64 v[142:143], 1, v[142:143]
	v_lshl_add_u64 v[150:151], v[150:151], 0, v[142:143]
	s_andn2_b64 vcc, exec, s[2:3]
	v_mul_f32_e32 v152, 0xbfb8aa3b, v126
	v_mul_f32_e32 v153, 0xbfb8aa3b, v127
	v_mul_f32_e32 v154, 0xbfb8aa3b, v128
	v_mul_f32_e32 v155, 0xbfb8aa3b, v129
	v_mul_f32_e32 v156, 0xbfb8aa3b, v118
	v_mul_f32_e32 v157, 0xbfb8aa3b, v119
	v_mul_f32_e32 v158, 0xbfb8aa3b, v120
	v_mul_f32_e32 v159, 0xbfb8aa3b, v121
	v_exp_f32_e32 v152, v152
	v_exp_f32_e32 v153, v153
	v_exp_f32_e32 v154, v154
	v_exp_f32_e32 v155, v155
	v_exp_f32_e32 v156, v156
	v_exp_f32_e32 v157, v157
	v_exp_f32_e32 v158, v158
	v_exp_f32_e32 v159, v159
	v_add_f32_e32 v152, 1.0, v152
	v_add_f32_e32 v153, 1.0, v153
	v_add_f32_e32 v154, 1.0, v154
	v_add_f32_e32 v155, 1.0, v155
	v_add_f32_e32 v156, 1.0, v156
	v_add_f32_e32 v157, 1.0, v157
	v_add_f32_e32 v158, 1.0, v158
	v_add_f32_e32 v159, 1.0, v159
	v_rcp_f32_e32 v152, v152
	v_rcp_f32_e32 v153, v153
	v_rcp_f32_e32 v154, v154
	v_rcp_f32_e32 v155, v155
	v_rcp_f32_e32 v156, v156
	v_rcp_f32_e32 v157, v157
	v_rcp_f32_e32 v158, v158
	v_rcp_f32_e32 v159, v159
	v_mul_f32_e32 v152, v126, v152
	v_mul_f32_e32 v153, v127, v153
	v_mul_f32_e32 v154, v128, v154
	v_mul_f32_e32 v155, v129, v155
	v_mul_f32_e32 v156, v118, v156
	v_mul_f32_e32 v157, v119, v157
	v_mul_f32_e32 v158, v120, v158
	v_mul_f32_e32 v159, v121, v159
	v_mul_f32_e32 v122, v122, v152
	v_mul_f32_e32 v123, v123, v153
	v_mul_f32_e32 v124, v124, v154
	v_mul_f32_e32 v125, v125, v155
	v_mul_f32_e32 v114, v114, v156
	v_mul_f32_e32 v115, v115, v157
	v_mul_f32_e32 v116, v116, v158
	v_mul_f32_e32 v117, v117, v159
	v_cvt_pk_bf16_f32 v122, v122, v123
	v_cvt_pk_bf16_f32 v123, v124, v125
	v_cvt_pk_bf16_f32 v114, v114, v115
	v_cvt_pk_bf16_f32 v115, v116, v117
	v_mul_f32_e32 v152, 0xbfb8aa3b, v110
	v_mul_f32_e32 v153, 0xbfb8aa3b, v111
	v_mul_f32_e32 v154, 0xbfb8aa3b, v112
	v_mul_f32_e32 v155, 0xbfb8aa3b, v113
	v_mul_f32_e32 v156, 0xbfb8aa3b, v102
	v_mul_f32_e32 v157, 0xbfb8aa3b, v103
	v_mul_f32_e32 v158, 0xbfb8aa3b, v104
	v_mul_f32_e32 v159, 0xbfb8aa3b, v105
	v_exp_f32_e32 v152, v152
	v_exp_f32_e32 v153, v153
	v_exp_f32_e32 v154, v154
	v_exp_f32_e32 v155, v155
	v_exp_f32_e32 v156, v156
	v_exp_f32_e32 v157, v157
	v_exp_f32_e32 v158, v158
	v_exp_f32_e32 v159, v159
	v_add_f32_e32 v152, 1.0, v152
	v_add_f32_e32 v153, 1.0, v153
	v_add_f32_e32 v154, 1.0, v154
	v_add_f32_e32 v155, 1.0, v155
	v_add_f32_e32 v156, 1.0, v156
	v_add_f32_e32 v157, 1.0, v157
	v_add_f32_e32 v158, 1.0, v158
	v_add_f32_e32 v159, 1.0, v159
	v_rcp_f32_e32 v152, v152
	v_rcp_f32_e32 v153, v153
	v_rcp_f32_e32 v154, v154
	v_rcp_f32_e32 v155, v155
	v_rcp_f32_e32 v156, v156
	v_rcp_f32_e32 v157, v157
	v_rcp_f32_e32 v158, v158
	v_rcp_f32_e32 v159, v159
	v_mul_f32_e32 v152, v110, v152
	v_mul_f32_e32 v153, v111, v153
	v_mul_f32_e32 v154, v112, v154
	v_mul_f32_e32 v155, v113, v155
	v_mul_f32_e32 v156, v102, v156
	v_mul_f32_e32 v157, v103, v157
	v_mul_f32_e32 v158, v104, v158
	v_mul_f32_e32 v159, v105, v159
	v_mul_f32_e32 v106, v106, v152
	v_mul_f32_e32 v107, v107, v153
	v_mul_f32_e32 v108, v108, v154
	v_mul_f32_e32 v109, v109, v155
	v_mul_f32_e32 v98, v98, v156
	v_mul_f32_e32 v99, v99, v157
	v_mul_f32_e32 v100, v100, v158
	v_mul_f32_e32 v101, v101, v159
	v_cvt_pk_bf16_f32 v106, v106, v107
	v_cvt_pk_bf16_f32 v107, v108, v109
	v_cvt_pk_bf16_f32 v98, v98, v99
	v_cvt_pk_bf16_f32 v99, v100, v101
	v_mul_f32_e32 v152, 0xbfb8aa3b, v92
	v_mul_f32_e32 v153, 0xbfb8aa3b, v93
	v_mul_f32_e32 v154, 0xbfb8aa3b, v94
	v_mul_f32_e32 v155, 0xbfb8aa3b, v95
	v_mul_f32_e32 v156, 0xbfb8aa3b, v84
	v_mul_f32_e32 v157, 0xbfb8aa3b, v85
	v_mul_f32_e32 v158, 0xbfb8aa3b, v86
	v_mul_f32_e32 v159, 0xbfb8aa3b, v87
	v_exp_f32_e32 v152, v152
	v_exp_f32_e32 v153, v153
	v_exp_f32_e32 v154, v154
	v_exp_f32_e32 v155, v155
	v_exp_f32_e32 v156, v156
	v_exp_f32_e32 v157, v157
	v_exp_f32_e32 v158, v158
	v_exp_f32_e32 v159, v159
	v_add_f32_e32 v152, 1.0, v152
	v_add_f32_e32 v153, 1.0, v153
	v_add_f32_e32 v154, 1.0, v154
	v_add_f32_e32 v155, 1.0, v155
	v_add_f32_e32 v156, 1.0, v156
	v_add_f32_e32 v157, 1.0, v157
	v_add_f32_e32 v158, 1.0, v158
	v_add_f32_e32 v159, 1.0, v159
	v_rcp_f32_e32 v152, v152
	v_rcp_f32_e32 v153, v153
	v_rcp_f32_e32 v154, v154
	v_rcp_f32_e32 v155, v155
	v_rcp_f32_e32 v156, v156
	v_rcp_f32_e32 v157, v157
	v_rcp_f32_e32 v158, v158
	v_rcp_f32_e32 v159, v159
	v_mul_f32_e32 v152, v92, v152
	v_mul_f32_e32 v153, v93, v153
	v_mul_f32_e32 v154, v94, v154
	v_mul_f32_e32 v155, v95, v155
	v_mul_f32_e32 v156, v84, v156
	v_mul_f32_e32 v157, v85, v157
	v_mul_f32_e32 v158, v86, v158
	v_mul_f32_e32 v159, v87, v159
	v_mul_f32_e32 v88, v88, v152
	v_mul_f32_e32 v89, v89, v153
	v_mul_f32_e32 v90, v90, v154
	v_mul_f32_e32 v91, v91, v155
	v_mul_f32_e32 v80, v80, v156
	v_mul_f32_e32 v81, v81, v157
	v_mul_f32_e32 v82, v82, v158
	v_mul_f32_e32 v83, v83, v159
	v_cvt_pk_bf16_f32 v88, v88, v89
	v_cvt_pk_bf16_f32 v89, v90, v91
	v_cvt_pk_bf16_f32 v80, v80, v81
	v_cvt_pk_bf16_f32 v81, v82, v83
	v_mul_f32_e32 v152, 0xbfb8aa3b, v76
	v_mul_f32_e32 v153, 0xbfb8aa3b, v77
	v_mul_f32_e32 v154, 0xbfb8aa3b, v78
	v_mul_f32_e32 v155, 0xbfb8aa3b, v79
	v_mul_f32_e32 v156, 0xbfb8aa3b, v68
	v_mul_f32_e32 v157, 0xbfb8aa3b, v69
	v_mul_f32_e32 v158, 0xbfb8aa3b, v70
	v_mul_f32_e32 v159, 0xbfb8aa3b, v71
	v_exp_f32_e32 v152, v152
	v_exp_f32_e32 v153, v153
	v_exp_f32_e32 v154, v154
	v_exp_f32_e32 v155, v155
	v_exp_f32_e32 v156, v156
	v_exp_f32_e32 v157, v157
	v_exp_f32_e32 v158, v158
	v_exp_f32_e32 v159, v159
	v_add_f32_e32 v152, 1.0, v152
	v_add_f32_e32 v153, 1.0, v153
	v_add_f32_e32 v154, 1.0, v154
	v_add_f32_e32 v155, 1.0, v155
	v_add_f32_e32 v156, 1.0, v156
	v_add_f32_e32 v157, 1.0, v157
	v_add_f32_e32 v158, 1.0, v158
	v_add_f32_e32 v159, 1.0, v159
	v_rcp_f32_e32 v152, v152
	v_rcp_f32_e32 v153, v153
	v_rcp_f32_e32 v154, v154
	v_rcp_f32_e32 v155, v155
	v_rcp_f32_e32 v156, v156
	v_rcp_f32_e32 v157, v157
	v_rcp_f32_e32 v158, v158
	v_rcp_f32_e32 v159, v159
	v_mul_f32_e32 v152, v76, v152
	v_mul_f32_e32 v153, v77, v153
	v_mul_f32_e32 v154, v78, v154
	v_mul_f32_e32 v155, v79, v155
	v_mul_f32_e32 v156, v68, v156
	v_mul_f32_e32 v157, v69, v157
	v_mul_f32_e32 v158, v70, v158
	v_mul_f32_e32 v159, v71, v159
	v_mul_f32_e32 v72, v72, v152
	v_mul_f32_e32 v73, v73, v153
	v_mul_f32_e32 v74, v74, v154
	v_mul_f32_e32 v75, v75, v155
	v_mul_f32_e32 v64, v64, v156
	v_mul_f32_e32 v65, v65, v157
	v_mul_f32_e32 v66, v66, v158
	v_mul_f32_e32 v67, v67, v159
	v_cvt_pk_bf16_f32 v72, v72, v73
	v_cvt_pk_bf16_f32 v73, v74, v75
	v_cvt_pk_bf16_f32 v64, v64, v65
	v_cvt_pk_bf16_f32 v65, v66, v67
	v_mul_f32_e32 v152, 0xbfb8aa3b, v60
	v_mul_f32_e32 v153, 0xbfb8aa3b, v61
	v_mul_f32_e32 v154, 0xbfb8aa3b, v62
	v_mul_f32_e32 v155, 0xbfb8aa3b, v63
	v_mul_f32_e32 v156, 0xbfb8aa3b, v52
	v_mul_f32_e32 v157, 0xbfb8aa3b, v53
	v_mul_f32_e32 v158, 0xbfb8aa3b, v54
	v_mul_f32_e32 v159, 0xbfb8aa3b, v55
	v_exp_f32_e32 v152, v152
	v_exp_f32_e32 v153, v153
	v_exp_f32_e32 v154, v154
	v_exp_f32_e32 v155, v155
	v_exp_f32_e32 v156, v156
	v_exp_f32_e32 v157, v157
	v_exp_f32_e32 v158, v158
	v_exp_f32_e32 v159, v159
	v_add_f32_e32 v152, 1.0, v152
	v_add_f32_e32 v153, 1.0, v153
	v_add_f32_e32 v154, 1.0, v154
	v_add_f32_e32 v155, 1.0, v155
	v_add_f32_e32 v156, 1.0, v156
	v_add_f32_e32 v157, 1.0, v157
	v_add_f32_e32 v158, 1.0, v158
	v_add_f32_e32 v159, 1.0, v159
	v_rcp_f32_e32 v152, v152
	v_rcp_f32_e32 v153, v153
	v_rcp_f32_e32 v154, v154
	v_rcp_f32_e32 v155, v155
	v_rcp_f32_e32 v156, v156
	v_rcp_f32_e32 v157, v157
	v_rcp_f32_e32 v158, v158
	v_rcp_f32_e32 v159, v159
	v_mul_f32_e32 v152, v60, v152
	v_mul_f32_e32 v153, v61, v153
	v_mul_f32_e32 v154, v62, v154
	v_mul_f32_e32 v155, v63, v155
	v_mul_f32_e32 v156, v52, v156
	v_mul_f32_e32 v157, v53, v157
	v_mul_f32_e32 v158, v54, v158
	v_mul_f32_e32 v159, v55, v159
	v_mul_f32_e32 v56, v56, v152
	v_mul_f32_e32 v57, v57, v153
	v_mul_f32_e32 v58, v58, v154
	v_mul_f32_e32 v59, v59, v155
	v_mul_f32_e32 v48, v48, v156
	v_mul_f32_e32 v49, v49, v157
	v_mul_f32_e32 v50, v50, v158
	v_mul_f32_e32 v51, v51, v159
	v_cvt_pk_bf16_f32 v56, v56, v57
	v_cvt_pk_bf16_f32 v57, v58, v59
	v_cvt_pk_bf16_f32 v48, v48, v49
	v_cvt_pk_bf16_f32 v49, v50, v51
	v_mul_f32_e32 v152, 0xbfb8aa3b, v44
	v_mul_f32_e32 v153, 0xbfb8aa3b, v45
	v_mul_f32_e32 v154, 0xbfb8aa3b, v46
	v_mul_f32_e32 v155, 0xbfb8aa3b, v47
	v_mul_f32_e32 v156, 0xbfb8aa3b, v36
	v_mul_f32_e32 v157, 0xbfb8aa3b, v37
	v_mul_f32_e32 v158, 0xbfb8aa3b, v38
	v_mul_f32_e32 v159, 0xbfb8aa3b, v39
	v_exp_f32_e32 v152, v152
	v_exp_f32_e32 v153, v153
	v_exp_f32_e32 v154, v154
	v_exp_f32_e32 v155, v155
	v_exp_f32_e32 v156, v156
	v_exp_f32_e32 v157, v157
	v_exp_f32_e32 v158, v158
	v_exp_f32_e32 v159, v159
	v_add_f32_e32 v152, 1.0, v152
	v_add_f32_e32 v153, 1.0, v153
	v_add_f32_e32 v154, 1.0, v154
	v_add_f32_e32 v155, 1.0, v155
	v_add_f32_e32 v156, 1.0, v156
	v_add_f32_e32 v157, 1.0, v157
	v_add_f32_e32 v158, 1.0, v158
	v_add_f32_e32 v159, 1.0, v159
	v_rcp_f32_e32 v152, v152
	v_rcp_f32_e32 v153, v153
	v_rcp_f32_e32 v154, v154
	v_rcp_f32_e32 v155, v155
	v_rcp_f32_e32 v156, v156
	v_rcp_f32_e32 v157, v157
	v_rcp_f32_e32 v158, v158
	v_rcp_f32_e32 v159, v159
	v_mul_f32_e32 v152, v44, v152
	v_mul_f32_e32 v153, v45, v153
	v_mul_f32_e32 v154, v46, v154
	v_mul_f32_e32 v155, v47, v155
	v_mul_f32_e32 v156, v36, v156
	v_mul_f32_e32 v157, v37, v157
	v_mul_f32_e32 v158, v38, v158
	v_mul_f32_e32 v159, v39, v159
	v_mul_f32_e32 v40, v40, v152
	v_mul_f32_e32 v41, v41, v153
	v_mul_f32_e32 v42, v42, v154
	v_mul_f32_e32 v43, v43, v155
	v_mul_f32_e32 v32, v32, v156
	v_mul_f32_e32 v33, v33, v157
	v_mul_f32_e32 v34, v34, v158
	v_mul_f32_e32 v35, v35, v159
	v_cvt_pk_bf16_f32 v40, v40, v41
	v_cvt_pk_bf16_f32 v41, v42, v43
	v_cvt_pk_bf16_f32 v32, v32, v33
	v_cvt_pk_bf16_f32 v33, v34, v35
	v_mul_f32_e32 v152, 0xbfb8aa3b, v28
	v_mul_f32_e32 v153, 0xbfb8aa3b, v29
	v_mul_f32_e32 v154, 0xbfb8aa3b, v30
	v_mul_f32_e32 v155, 0xbfb8aa3b, v31
	v_mul_f32_e32 v156, 0xbfb8aa3b, v20
	v_mul_f32_e32 v157, 0xbfb8aa3b, v21
	v_mul_f32_e32 v158, 0xbfb8aa3b, v22
	v_mul_f32_e32 v159, 0xbfb8aa3b, v23
	v_exp_f32_e32 v152, v152
	v_exp_f32_e32 v153, v153
	v_exp_f32_e32 v154, v154
	v_exp_f32_e32 v155, v155
	v_exp_f32_e32 v156, v156
	v_exp_f32_e32 v157, v157
	v_exp_f32_e32 v158, v158
	v_exp_f32_e32 v159, v159
	v_add_f32_e32 v152, 1.0, v152
	v_add_f32_e32 v153, 1.0, v153
	v_add_f32_e32 v154, 1.0, v154
	v_add_f32_e32 v155, 1.0, v155
	v_add_f32_e32 v156, 1.0, v156
	v_add_f32_e32 v157, 1.0, v157
	v_add_f32_e32 v158, 1.0, v158
	v_add_f32_e32 v159, 1.0, v159
	v_rcp_f32_e32 v152, v152
	v_rcp_f32_e32 v153, v153
	v_rcp_f32_e32 v154, v154
	v_rcp_f32_e32 v155, v155
	v_rcp_f32_e32 v156, v156
	v_rcp_f32_e32 v157, v157
	v_rcp_f32_e32 v158, v158
	v_rcp_f32_e32 v159, v159
	v_mul_f32_e32 v152, v28, v152
	v_mul_f32_e32 v153, v29, v153
	v_mul_f32_e32 v154, v30, v154
	v_mul_f32_e32 v155, v31, v155
	v_mul_f32_e32 v156, v20, v156
	v_mul_f32_e32 v157, v21, v157
	v_mul_f32_e32 v158, v22, v158
	v_mul_f32_e32 v159, v23, v159
	v_mul_f32_e32 v24, v24, v152
	v_mul_f32_e32 v25, v25, v153
	v_mul_f32_e32 v26, v26, v154
	v_mul_f32_e32 v27, v27, v155
	v_mul_f32_e32 v16, v16, v156
	v_mul_f32_e32 v17, v17, v157
	v_mul_f32_e32 v18, v18, v158
	v_mul_f32_e32 v19, v19, v159
	v_cvt_pk_bf16_f32 v24, v24, v25
	v_cvt_pk_bf16_f32 v25, v26, v27
	v_cvt_pk_bf16_f32 v16, v16, v17
	v_cvt_pk_bf16_f32 v17, v18, v19
	s_mov_b64 s[24:25], -1
	v_mul_f32_e32 v152, 0xbfb8aa3b, v12
	v_mul_f32_e32 v153, 0xbfb8aa3b, v13
	v_mul_f32_e32 v154, 0xbfb8aa3b, v14
	v_mul_f32_e32 v155, 0xbfb8aa3b, v15
	v_mul_f32_e32 v156, 0xbfb8aa3b, v4
	v_mul_f32_e32 v157, 0xbfb8aa3b, v5
	v_mul_f32_e32 v158, 0xbfb8aa3b, v6
	v_mul_f32_e32 v159, 0xbfb8aa3b, v7
	v_exp_f32_e32 v152, v152
	v_exp_f32_e32 v153, v153
	v_exp_f32_e32 v154, v154
	v_exp_f32_e32 v155, v155
	v_exp_f32_e32 v156, v156
	v_exp_f32_e32 v157, v157
	v_exp_f32_e32 v158, v158
	v_exp_f32_e32 v159, v159
	v_add_f32_e32 v152, 1.0, v152
	v_add_f32_e32 v153, 1.0, v153
	v_add_f32_e32 v154, 1.0, v154
	v_add_f32_e32 v155, 1.0, v155
	v_add_f32_e32 v156, 1.0, v156
	v_add_f32_e32 v157, 1.0, v157
	v_add_f32_e32 v158, 1.0, v158
	v_add_f32_e32 v159, 1.0, v159
	v_rcp_f32_e32 v152, v152
	v_rcp_f32_e32 v153, v153
	v_rcp_f32_e32 v154, v154
	v_rcp_f32_e32 v155, v155
	v_rcp_f32_e32 v156, v156
	v_rcp_f32_e32 v157, v157
	v_rcp_f32_e32 v158, v158
	v_rcp_f32_e32 v159, v159
	v_mul_f32_e32 v152, v12, v152
	v_mul_f32_e32 v153, v13, v153
	v_mul_f32_e32 v154, v14, v154
	v_mul_f32_e32 v155, v15, v155
	v_mul_f32_e32 v156, v4, v156
	v_mul_f32_e32 v157, v5, v157
	v_mul_f32_e32 v158, v6, v158
	v_mul_f32_e32 v159, v7, v159
	v_mul_f32_e32 v8, v8, v152
	v_mul_f32_e32 v9, v9, v153
	v_mul_f32_e32 v10, v10, v154
	v_mul_f32_e32 v11, v11, v155
	v_mul_f32_e32 v0, v0, v156
	v_mul_f32_e32 v1, v1, v157
	v_mul_f32_e32 v2, v2, v158
	v_mul_f32_e32 v3, v3, v159
	v_cvt_pk_bf16_f32 v8, v8, v9
	v_cvt_pk_bf16_f32 v9, v10, v11
	v_cvt_pk_bf16_f32 v0, v0, v1
	v_cvt_pk_bf16_f32 v1, v2, v3
	v_and_b32_e32 v160, 7, v144
	v_lshlrev_b32_e32 v160, 1, v160
	s_lshl_b32 s100, s79, 2
	v_add_u32_e32 v161, s100, v145
	v_xor_b32_e32 v161, v161, v160
	v_lshlrev_b32_e32 v161, 3, v161
	v_lshl_add_u32 v161, v144, 8, v161
	s_lshl_b32 s100, s62, 13
	s_add_i32 s100, s100, 49152
	v_add_u32_e32 v161, s100, v161
	v_add_u32_e32 v167, 98304, v161
	v_xor_b32_e32 v162, v144, v145
	v_lshlrev_b32_e32 v162, 4, v162
	s_lshl_b32 s101, s79, 11
	s_add_i32 s101, s101, s100
	v_lshl_add_u32 v163, v145, 8, s101
	v_add_u32_e32 v164, v163, v162
	v_or_b32_e32 v165, 4, v145
	v_xor_b32_e32 v165, v144, v165
	v_lshl_add_u32 v165, v165, 4, v163
	v_add_u32_e32 v174, 98304, v164
	v_add_u32_e32 v175, 98304, v165
	v_sub_u32_e32 v166, v148, v144
	s_lshl_b32 s101, s79, 3
	v_add3_u32 v166, v166, s101, v145
	v_mov_b64_e32 v[170:171], s[6:7]
	v_mad_u64_u32 v[168:169], s[100:101], v166, s47, v[170:171]
	s_lshl_b32 s101, s79, 5
	v_subrev_u32_e32 v172, s101, v142
	v_lshlrev_b32_e32 v173, 3, v145
	v_sub_u32_e32 v172, v172, v173
	v_lshl_add_u32 v172, v144, 4, v172
	v_mov_b32_e32 v173, 0
	v_lshl_add_u64 v[168:169], v[168:169], 0, v[172:173]
	s_mov_b32 s101, 0
	ds_write_b64 v161, v[122:123] offset:0
	ds_write_b64 v161, v[114:115] offset:128
	ds_write_b64 v161, v[106:107] offset:4096
	ds_write_b64 v161, v[98:99] offset:4224
	s_waitcnt lgkmcnt(0)
	s_barrier
	ds_read_b128 v[176:179], v164
	ds_read_b128 v[180:183], v165 offset:1024
	s_waitcnt lgkmcnt(1)
	global_store_dwordx4 v[168:169], v[176:179], off
	s_mov_b32 s100, 22528
	v_lshl_add_u64 v[168:169], v[168:169], 0, s[100:101]
	s_waitcnt lgkmcnt(0)
	global_store_dwordx4 v[168:169], v[180:183], off
	s_mov_b32 s100, 157696
	v_lshl_add_u64 v[168:169], v[168:169], 0, s[100:101]
	s_nop 1
	ds_write_b64 v167, v[88:89] offset:0
	ds_write_b64 v167, v[80:81] offset:128
	ds_write_b64 v167, v[72:73] offset:4096
	ds_write_b64 v167, v[64:65] offset:4224
	s_waitcnt lgkmcnt(0)
	s_barrier
	ds_read_b128 v[176:179], v174
	ds_read_b128 v[180:183], v175 offset:1024
	s_waitcnt lgkmcnt(1)
	global_store_dwordx4 v[168:169], v[176:179], off
	s_mov_b32 s100, 22528
	v_lshl_add_u64 v[168:169], v[168:169], 0, s[100:101]
	s_waitcnt lgkmcnt(0)
	global_store_dwordx4 v[168:169], v[180:183], off
	s_mov_b32 s100, 518144
	v_lshl_add_u64 v[168:169], v[168:169], 0, s[100:101]
	s_nop 1
	ds_write_b64 v161, v[56:57] offset:0
	ds_write_b64 v161, v[48:49] offset:128
	ds_write_b64 v161, v[40:41] offset:4096
	ds_write_b64 v161, v[32:33] offset:4224
	s_waitcnt lgkmcnt(0)
	s_barrier
	ds_read_b128 v[176:179], v164
	ds_read_b128 v[180:183], v165 offset:1024
	s_waitcnt lgkmcnt(1)
	global_store_dwordx4 v[168:169], v[176:179], off
	s_mov_b32 s100, 22528
	v_lshl_add_u64 v[168:169], v[168:169], 0, s[100:101]
	s_waitcnt lgkmcnt(0)
	global_store_dwordx4 v[168:169], v[180:183], off
	s_mov_b32 s100, 157696
	v_lshl_add_u64 v[168:169], v[168:169], 0, s[100:101]
	s_nop 1
	ds_write_b64 v167, v[24:25] offset:0
	ds_write_b64 v167, v[16:17] offset:128
	ds_write_b64 v167, v[8:9] offset:4096
	ds_write_b64 v167, v[0:1] offset:4224
	s_waitcnt lgkmcnt(0)
	s_barrier
	ds_read_b128 v[176:179], v174
	ds_read_b128 v[180:183], v175 offset:1024
	s_waitcnt lgkmcnt(1)
	global_store_dwordx4 v[168:169], v[176:179], off
	s_mov_b32 s100, 22528
	v_lshl_add_u64 v[168:169], v[168:169], 0, s[100:101]
	s_waitcnt lgkmcnt(0)
	global_store_dwordx4 v[168:169], v[180:183], off
	s_nop 1
	s_cbranch_vccnz .LBB0_729
	s_andn2_b64 vcc, exec, s[4:5]
	s_cbranch_vccnz .LBB0_728
	s_barrier
	s_branch .LBB0_728

	.amdhsa_kernel _Z8mega_fwd6Params
		.amdhsa_group_segment_fixed_size 16384
		.amdhsa_private_segment_fixed_size 0
		.amdhsa_kernarg_size 400
		.amdhsa_user_sgpr_count 2
		.amdhsa_user_sgpr_dispatch_ptr 0
		.amdhsa_user_sgpr_queue_ptr 0
		.amdhsa_user_sgpr_kernarg_segment_ptr 1
		.amdhsa_user_sgpr_dispatch_id 0
		.amdhsa_user_sgpr_kernarg_preload_length 0
		.amdhsa_user_sgpr_kernarg_preload_offset 0
		.amdhsa_user_sgpr_private_segment_size 0
		.amdhsa_uses_dynamic_stack 0
		.amdhsa_enable_private_segment 0
		.amdhsa_system_sgpr_workgroup_id_x 1
		.amdhsa_system_sgpr_workgroup_id_y 0
		.amdhsa_system_sgpr_workgroup_id_z 0
		.amdhsa_system_sgpr_workgroup_info 0
		.amdhsa_system_vgpr_workitem_id 2
		.amdhsa_next_free_vgpr 256
		.amdhsa_next_free_sgpr 102
		.amdhsa_accum_offset 256
		.amdhsa_reserve_vcc 1
		.amdhsa_float_round_mode_32 0
		.amdhsa_float_round_mode_16_64 0
		.amdhsa_float_denorm_mode_32 3
		.amdhsa_float_denorm_mode_16_64 3
		.amdhsa_dx10_clamp 1
		.amdhsa_ieee_mode 1
		.amdhsa_fp16_overflow 0
		.amdhsa_tg_split 0
		.amdhsa_exception_fp_ieee_invalid_op 0
		.amdhsa_exception_fp_denorm_src 0
		.amdhsa_exception_fp_ieee_div_zero 0
		.amdhsa_exception_fp_ieee_overflow 0
		.amdhsa_exception_fp_ieee_underflow 0
		.amdhsa_exception_fp_ieee_inexact 0
		.amdhsa_exception_int_div_zero 0
	.end_amdhsa_kernel

amdhsa.kernels:
  - .agpr_count:     0
    .args:
      - .offset:         0
        .size:           144
        .value_kind:     by_value
      - .offset:         144
        .size:           4
        .value_kind:     hidden_block_count_x
      - .offset:         148
        .size:           4
        .value_kind:     hidden_block_count_y
      - .offset:         152
        .size:           4
        .value_kind:     hidden_block_count_z
      - .offset:         156
        .size:           2
        .value_kind:     hidden_group_size_x
      - .offset:         158
        .size:           2
        .value_kind:     hidden_group_size_y
      - .offset:         160
        .size:           2
        .value_kind:     hidden_group_size_z
      - .offset:         162
        .size:           2
        .value_kind:     hidden_remainder_x
      - .offset:         164
        .size:           2
        .value_kind:     hidden_remainder_y
      - .offset:         166
        .size:           2
        .value_kind:     hidden_remainder_z
      - .offset:         184
        .size:           8
        .value_kind:     hidden_global_offset_x
      - .offset:         192
        .size:           8
        .value_kind:     hidden_global_offset_y
      - .offset:         200
        .size:           8
        .value_kind:     hidden_global_offset_z
      - .offset:         208
        .size:           2
        .value_kind:     hidden_grid_dims
      - .offset:         232
        .size:           8
        .value_kind:     hidden_multigrid_sync_arg
      - .offset:         264
        .size:           4
        .value_kind:     hidden_dynamic_lds_size
    .group_segment_fixed_size: 16384
    .kernarg_segment_align: 8
    .kernarg_segment_size: 400
    .language:       OpenCL C
    .language_version:
      - 2
      - 0
    .max_flat_workgroup_size: 512
    .name:           _Z8mega_fwd6Params
    .private_segment_fixed_size: 0
    .sgpr_count:     108
    .sgpr_spill_count: 16
    .symbol:         _Z8mega_fwd6Params.kd
    .uniform_work_group_size: 1
    .uses_dynamic_stack: false
    .vgpr_count:     256
    .vgpr_spill_count: 0
    .wavefront_size: 64
